# P3 w_up/w_down transposes: hand-written deep-prefetch routine, run only by the 128 WGs without a quarter tile
# speedup vs baseline: 1.0147x; 1.0037x over previous
; #define LAS __attribute__((address_space(3)))
; __device__ __forceinline__ unsigned cvtpk(float lo, float hi) { f32x2_t v = {lo, hi}; bf16x2_t b = __builtin_convertvector(v, bf16x2_t); return __builtin_bit_cast(unsigned, b); }
; template <int MODE>
; __device__ __forceinline__ void transpose_item(const float* W, int N, bf16_t* WT, int ldt, int coff, LAS float* scr, int item, int lane, const float* g) {
;     const int nblk = N / 32, kb = item / nblk, nb = item % nblk, k0 = 64 * kb, n0 = 32 * nb;
; #pragma unroll 8
;     for (int i = 0; i < 32; ++i) { const int kk = 2 * i + (lane >> 5); float v = W[(size_t)(k0 + kk) * N + n0 + (lane & 31)]; if (MODE >= 1) v *= g[k0 + kk]; scr[kk * 33 + (lane & 31)] = v; }
;     asm volatile("s_waitcnt lgkmcnt(0)" ::: "memory");
;     const int c = lane & 7;
; #pragma unroll
;     for (int j = 0; j < 4; ++j) {
;         const int n = (lane >> 3) + 8 * j; const LAS float* s = scr + (8 * c) * 33 + n;
;         u32x4 o; o.x = cvtpk(s[0 * 33], s[1 * 33]); o.y = cvtpk(s[2 * 33], s[3 * 33]); o.z = cvtpk(s[4 * 33], s[5 * 33]); o.w = cvtpk(s[6 * 33], s[7 * 33]);
;         int dr = n0 + n;
;         if (MODE == 1) { dr = (dr < DFF) ? 256 * (dr >> 7) + (dr & 127) : 256 * ((dr - DFF) >> 7) + 128 + ((dr - DFF) & 127); }
;         if (MODE == 2) {
;             if (dr >= 6144) { const int t = dr - 6144, ch = t & 2047; dr = 6144 + 256 * (ch >> 7) + ((t >> 11) << 7) + (ch & 127); }
; __global__ void __launch_bounds__(512, 2) mk_fwd(Args a) {
;     ...
;     if (IN(3)) {
;         constexpr int I_U = 32 * 352, I_D = 88 * 64;
;         for (int it = gw; it < I_U + I_D; it += NGW) {
;             if (it < I_U) transpose_item<1>(a.in[I_WUP], 2 * DFF, WUP, DM, 0, scr, it, lane, a.in[I_N2]);
;             else transpose_item<0>(a.in[I_WDN], DM, WDN, DFF, 0, scr, it - I_U, lane, nullptr);
;         }
;         __syncthreads();
;         pg8::Gemm g{OOB, WAB, DM, DM, 1024}; pg8::StaticOrder S; S.init(MTOT / 256, DM / 256, G, bx, QLIM);
.LBB0_642:
	s_cmp_lt_i32 s70, 4
	s_cselect_b64 s[4:5], -1, 0
	s_add_u32 s44, s68, 0x1af00000
	s_addc_u32 s45, s69, 0
	s_add_u32 s6, s68, 0x1db00000
	s_addc_u32 s7, s69, 0
	v_writelane_b32 v250, s6, 20
	s_cmpk_lg_i32 s3, 0x100
	s_movk_i32 s8, 0x200
	v_writelane_b32 v250, s7, 21
	s_cselect_b64 s[6:7], -1, 0
	v_writelane_b32 v250, s6, 26
	s_cmpk_eq_i32 s3, 0x100
	s_nop 0
	v_writelane_b32 v250, s7, 27
	s_cselect_b64 s[6:7], -1, 0
	v_writelane_b32 v250, s6, 24
	s_nop 1
	v_writelane_b32 v250, s7, 25
	s_and_b64 s[6:7], s[6:7], exec
	s_cselect_b32 s88, s8, 0x7fffffff
	s_and_b64 s[4:5], s[4:5], s[0:1]
	s_andn2_b64 vcc, exec, s[4:5]
	s_cbranch_vccnz .LBB0_712
	s_cmpk_lt_i32 s96, 0x400
	s_cbranch_scc1 .LBB0_670
	s_and_b32 s0, s96, 7
	s_lshl_b32 s0, s0, 14
	v_readlane_b32 s6, v250, 20
	v_readlane_b32 s7, v250, 21
	s_add_i32 s1, s96, 0xfffffc00
	s_cmp_lt_u32 s1, 0x2c00
	s_cbranch_scc0 .Ltr_done_p3up
	v_lshrrev_b32_e32 v168, 3, v220
	v_and_b32_e32 v169, 7, v220
	v_mul_u32_u24_e32 v170, 0xb000, v168
	v_lshl_add_u32 v171, v169, 4, v170
	v_add_u32_e32 v172, 0x58000, v171
	v_add_u32_e32 v173, 0xb0000, v171
	v_add_u32_e32 v174, 0x108000, v171
	v_add_u32_e32 v175, 0x160000, v171
	v_add_u32_e32 v177, 0x1b8000, v171
	v_add_u32_e32 v182, 0x210000, v171
	v_add_u32_e32 v183, 0x268000, v171
	v_mul_u32_u24_e32 v170, 0x84, v168
	v_lshl_add_u32 v170, v169, 4, v170
	v_add_u32_e32 v189, s0, v170
	v_mul_u32_u24_e32 v170, 0x420, v169
	v_lshl_add_u32 v170, v168, 2, v170
	v_add_u32_e32 v190, s0, v170
	v_mul_u32_u24_e32 v170, 0x1000, v168
	v_lshl_add_u32 v184, v169, 4, v170
	v_add_u32_e32 v185, 0x8000, v184
	v_add_u32_e32 v186, 0x10000, v184
	v_add_u32_e32 v188, 0x18000, v184
	v_lshlrev_b32_e32 v191, 5, v169
	s_mov_b32 s10, s1
	s_mov_b32 s9, s1
	s_lshr_b32 s11, s9, 5
	s_mul_hi_u32 s11, s11, 0xba2e8ba3
	s_lshr_b32 s11, s11, 3
	s_mul_i32 s36, s11, 0x160
	s_sub_u32 s36, s9, s36
	s_mul_i32 s37, s11, 0x2c0000
	s_lshl_b32 s36, s36, 7
	s_add_u32 s37, s37, s36
	s_add_u32 s14, s22, s37
	s_addc_u32 s15, s23, 0
	global_load_dwordx4 v[0:3], v171, s[14:15]
	global_load_dwordx4 v[4:7], v172, s[14:15]
	global_load_dwordx4 v[8:11], v173, s[14:15]
	global_load_dwordx4 v[12:15], v174, s[14:15]
	global_load_dwordx4 v[16:19], v175, s[14:15]
	global_load_dwordx4 v[20:23], v177, s[14:15]
	global_load_dwordx4 v[24:27], v182, s[14:15]
	global_load_dwordx4 v[28:31], v183, s[14:15]
	s_lshl_b32 s37, s11, 8
	s_add_u32 s34, s20, s37
	s_addc_u32 s35, s21, 0
	global_load_dwordx4 v[144:147], v191, s[34:35]
	global_load_dwordx4 v[148:151], v191, s[34:35] offset:16
	s_add_u32 s9, s9, 0x400
	s_cmp_lt_u32 s9, 0x2c00
	s_cbranch_scc0 .Ltr_p1_p3up
	s_lshr_b32 s11, s9, 5
	s_mul_hi_u32 s11, s11, 0xba2e8ba3
	s_lshr_b32 s11, s11, 3
	s_mul_i32 s36, s11, 0x160
	s_sub_u32 s36, s9, s36
	s_mul_i32 s37, s11, 0x2c0000
	s_lshl_b32 s36, s36, 7
	s_add_u32 s37, s37, s36
	s_add_u32 s14, s22, s37
	s_addc_u32 s15, s23, 0
	global_load_dwordx4 v[32:35], v171, s[14:15]
	global_load_dwordx4 v[36:39], v172, s[14:15]
	global_load_dwordx4 v[40:43], v173, s[14:15]
	global_load_dwordx4 v[44:47], v174, s[14:15]
	global_load_dwordx4 v[48:51], v175, s[14:15]
	global_load_dwordx4 v[52:55], v177, s[14:15]
	global_load_dwordx4 v[56:59], v182, s[14:15]
	global_load_dwordx4 v[60:63], v183, s[14:15]
	s_lshl_b32 s37, s11, 8
	s_add_u32 s34, s20, s37
	s_addc_u32 s35, s21, 0
	global_load_dwordx4 v[152:155], v191, s[34:35]
	global_load_dwordx4 v[156:159], v191, s[34:35] offset:16
.Ltr_p1_p3up:
	s_add_u32 s9, s9, 0x400
.Ltr_st0_p3up:
	s_cmp_lt_u32 s9, 0x2c00
	s_cbranch_scc0 .Ltr_nl0_p3up
	s_lshr_b32 s11, s9, 5
	s_mul_hi_u32 s11, s11, 0xba2e8ba3
	s_lshr_b32 s11, s11, 3
	s_mul_i32 s36, s11, 0x160
	s_sub_u32 s36, s9, s36
	s_mul_i32 s37, s11, 0x2c0000
	s_lshl_b32 s36, s36, 7
	s_add_u32 s37, s37, s36
	s_add_u32 s14, s22, s37
	s_addc_u32 s15, s23, 0
	global_load_dwordx4 v[64:67], v171, s[14:15]
	global_load_dwordx4 v[68:71], v172, s[14:15]
	global_load_dwordx4 v[72:75], v173, s[14:15]
	global_load_dwordx4 v[76:79], v174, s[14:15]
	global_load_dwordx4 v[80:83], v175, s[14:15]
	global_load_dwordx4 v[84:87], v177, s[14:15]
	global_load_dwordx4 v[88:91], v182, s[14:15]
	global_load_dwordx4 v[92:95], v183, s[14:15]
	s_lshl_b32 s37, s11, 8
	s_add_u32 s34, s20, s37
	s_addc_u32 s35, s21, 0
	global_load_dwordx4 v[160:163], v191, s[34:35]
	global_load_dwordx4 v[164:167], v191, s[34:35] offset:16
	s_waitcnt vmcnt(20)
	s_branch .Ltr_pr0_p3up
.Ltr_nl0_p3up:
	s_sub_u32 s11, s9, 0x400
	s_cmp_lt_u32 s11, 0x2c00
	s_cbranch_scc0 .Ltr_w00_p3up
	s_waitcnt vmcnt(10)
	s_branch .Ltr_pr0_p3up

; #define LAS __attribute__((address_space(3)))
; __device__ __forceinline__ unsigned cvtpk(float lo, float hi) { f32x2_t v = {lo, hi}; bf16x2_t b = __builtin_convertvector(v, bf16x2_t); return __builtin_bit_cast(unsigned, b); }
; template <int MODE>
; __device__ __forceinline__ void transpose_item(const float* W, int N, bf16_t* WT, int ldt, int coff, LAS float* scr, int item, int lane, const float* g) {
;     const int nblk = N / 32, kb = item / nblk, nb = item % nblk, k0 = 64 * kb, n0 = 32 * nb;
; #pragma unroll 8
;     for (int i = 0; i < 32; ++i) { const int kk = 2 * i + (lane >> 5); float v = W[(size_t)(k0 + kk) * N + n0 + (lane & 31)]; if (MODE >= 1) v *= g[k0 + kk]; scr[kk * 33 + (lane & 31)] = v; }
;     asm volatile("s_waitcnt lgkmcnt(0)" ::: "memory");
;     const int c = lane & 7;
; #pragma unroll
;     for (int j = 0; j < 4; ++j) {
;         const int n = (lane >> 3) + 8 * j; const LAS float* s = scr + (8 * c) * 33 + n;
;         u32x4 o; o.x = cvtpk(s[0 * 33], s[1 * 33]); o.y = cvtpk(s[2 * 33], s[3 * 33]); o.z = cvtpk(s[4 * 33], s[5 * 33]); o.w = cvtpk(s[6 * 33], s[7 * 33]);
;         int dr = n0 + n;
;         if (MODE == 1) { dr = (dr < DFF) ? 256 * (dr >> 7) + (dr & 127) : 256 * ((dr - DFF) >> 7) + 128 + ((dr - DFF) & 127); }
;         if (MODE == 2) {
;             if (dr >= 6144) { const int t = dr - 6144, ch = t & 2047; dr = 6144 + 256 * (ch >> 7) + ((t >> 11) << 7) + (ch & 127); }
;             else if (dr >= 4096) { const int t = dr - 4096, ch = t & 1023; dr = 4096 + 256 * (ch >> 7) + ((t >> 10) << 7) + (ch & 127); }
;         }
;         *(u32x4*)(WT + (size_t)dr * ldt + coff + k0 + 8 * c) = o;
;     }
;     asm volatile("s_waitcnt lgkmcnt(0)" ::: "memory");
; }
.Ltr_pr0_p3up:
	s_add_u32 s9, s9, 0x400
	s_lshr_b32 s11, s10, 5
	s_mul_hi_u32 s11, s11, 0xba2e8ba3
	s_lshr_b32 s11, s11, 3
	s_mul_i32 s36, s11, 0x160
	s_sub_u32 s36, s10, s36
	s_cmp_ge_u32 s36, 0xb0
	s_cselect_b32 s37, 0xb0, 0
	s_cselect_b32 s40, 0x80, 0
	s_sub_u32 s36, s36, s37
	s_lshl_b32 s36, s36, 5
	s_and_b32 s37, s36, 0xffffff80
	s_and_b32 s36, s36, 0x7f
	s_lshl_b32 s37, s37, 1
	s_add_u32 s37, s37, s36
	s_add_u32 s37, s37, s40
	s_mul_i32 s37, s37, 0x1000
	s_lshl_b32 s11, s11, 7
	s_add_u32 s37, s37, s11
	s_add_u32 s32, s44, s37
	s_addc_u32 s33, s45, 0
	ds_write_b32 v189, v0 offset:0
	ds_write_b32 v189, v1 offset:4
	ds_write_b32 v189, v2 offset:8
	ds_write_b32 v189, v3 offset:12
	ds_write_b32 v189, v4 offset:1056
	ds_write_b32 v189, v5 offset:1060
	ds_write_b32 v189, v6 offset:1064
	ds_write_b32 v189, v7 offset:1068
	ds_write_b32 v189, v8 offset:2112
	ds_write_b32 v189, v9 offset:2116
	ds_write_b32 v189, v10 offset:2120
	ds_write_b32 v189, v11 offset:2124
	ds_write_b32 v189, v12 offset:3168
	ds_write_b32 v189, v13 offset:3172
	ds_write_b32 v189, v14 offset:3176
	ds_write_b32 v189, v15 offset:3180
	ds_write_b32 v189, v16 offset:4224
	ds_write_b32 v189, v17 offset:4228
	ds_write_b32 v189, v18 offset:4232
	ds_write_b32 v189, v19 offset:4236
	ds_write_b32 v189, v20 offset:5280
	ds_write_b32 v189, v21 offset:5284
	ds_write_b32 v189, v22 offset:5288
	ds_write_b32 v189, v23 offset:5292
	ds_write_b32 v189, v24 offset:6336
	ds_write_b32 v189, v25 offset:6340
	ds_write_b32 v189, v26 offset:6344
	ds_write_b32 v189, v27 offset:6348
	ds_write_b32 v189, v28 offset:7392
	ds_write_b32 v189, v29 offset:7396
	ds_write_b32 v189, v30 offset:7400
	ds_write_b32 v189, v31 offset:7404
	s_waitcnt lgkmcnt(0)
	ds_read2_b32 v[96:97], v190 offset0:0 offset1:8
	ds_read2_b32 v[100:101], v190 offset0:33 offset1:41
	ds_read2_b32 v[104:105], v190 offset0:66 offset1:74
	ds_read2_b32 v[108:109], v190 offset0:99 offset1:107
	ds_read2_b32 v[112:113], v190 offset0:132 offset1:140
	ds_read2_b32 v[116:117], v190 offset0:165 offset1:173
	ds_read2_b32 v[120:121], v190 offset0:198 offset1:206
	ds_read2_b32 v[124:125], v190 offset0:231 offset1:239
	ds_read2_b32 v[98:99], v190 offset0:16 offset1:24
	ds_read2_b32 v[102:103], v190 offset0:49 offset1:57
	ds_read2_b32 v[106:107], v190 offset0:82 offset1:90
	ds_read2_b32 v[110:111], v190 offset0:115 offset1:123
	ds_read2_b32 v[114:115], v190 offset0:148 offset1:156
	ds_read2_b32 v[118:119], v190 offset0:181 offset1:189
	ds_read2_b32 v[122:123], v190 offset0:214 offset1:222
	ds_read2_b32 v[126:127], v190 offset0:247 offset1:255
	s_waitcnt lgkmcnt(0)
	v_mul_f32_e32 v96, v144, v96
	v_mul_f32_e32 v97, v144, v97
	v_mul_f32_e32 v98, v144, v98
	v_mul_f32_e32 v99, v144, v99
	v_mul_f32_e32 v100, v145, v100
	v_mul_f32_e32 v101, v145, v101
	v_mul_f32_e32 v102, v145, v102
	v_mul_f32_e32 v103, v145, v103
	v_mul_f32_e32 v104, v146, v104
	v_mul_f32_e32 v105, v146, v105
	v_mul_f32_e32 v106, v146, v106
	v_mul_f32_e32 v107, v146, v107
	v_mul_f32_e32 v108, v147, v108
	v_mul_f32_e32 v109, v147, v109
	v_mul_f32_e32 v110, v147, v110
	v_mul_f32_e32 v111, v147, v111
	v_mul_f32_e32 v112, v148, v112
	v_mul_f32_e32 v113, v148, v113
	v_mul_f32_e32 v114, v148, v114
	v_mul_f32_e32 v115, v148, v115
	v_mul_f32_e32 v116, v149, v116
	v_mul_f32_e32 v117, v149, v117
	v_mul_f32_e32 v118, v149, v118
	v_mul_f32_e32 v119, v149, v119
	v_mul_f32_e32 v120, v150, v120
	v_mul_f32_e32 v121, v150, v121
	v_mul_f32_e32 v122, v150, v122
	v_mul_f32_e32 v123, v150, v123
	v_mul_f32_e32 v124, v151, v124
	v_mul_f32_e32 v125, v151, v125
	v_mul_f32_e32 v126, v151, v126
	v_mul_f32_e32 v127, v151, v127
	v_cvt_pk_bf16_f32 v128, v96, v100
	v_cvt_pk_bf16_f32 v129, v104, v108
	v_cvt_pk_bf16_f32 v130, v112, v116
	v_cvt_pk_bf16_f32 v131, v120, v124
	global_store_dwordx4 v184, v[128:131], s[32:33]
	v_cvt_pk_bf16_f32 v132, v97, v101
	v_cvt_pk_bf16_f32 v133, v105, v109
	v_cvt_pk_bf16_f32 v134, v113, v117
	v_cvt_pk_bf16_f32 v135, v121, v125
	global_store_dwordx4 v185, v[132:135], s[32:33]
	v_cvt_pk_bf16_f32 v136, v98, v102
	v_cvt_pk_bf16_f32 v137, v106, v110
	v_cvt_pk_bf16_f32 v138, v114, v118
	v_cvt_pk_bf16_f32 v139, v122, v126
	global_store_dwordx4 v186, v[136:139], s[32:33]
	v_cvt_pk_bf16_f32 v140, v99, v103
	v_cvt_pk_bf16_f32 v141, v107, v111
	v_cvt_pk_bf16_f32 v142, v115, v119
	v_cvt_pk_bf16_f32 v143, v123, v127
	global_store_dwordx4 v188, v[140:143], s[32:33]
	s_add_u32 s10, s10, 0x400
	s_cmp_lt_u32 s10, 0x2c00
	s_cbranch_scc0 .Ltr_done_p3up
.Ltr_st1_p3up:
	s_cmp_lt_u32 s9, 0x2c00
	s_cbranch_scc0 .Ltr_nl1_p3up
	s_lshr_b32 s11, s9, 5
	s_mul_hi_u32 s11, s11, 0xba2e8ba3
	s_lshr_b32 s11, s11, 3
	s_mul_i32 s36, s11, 0x160
	s_sub_u32 s36, s9, s36
	s_mul_i32 s37, s11, 0x2c0000
	s_lshl_b32 s36, s36, 7
	s_add_u32 s37, s37, s36
	s_add_u32 s14, s22, s37
	s_addc_u32 s15, s23, 0
	global_load_dwordx4 v[0:3], v171, s[14:15]
	global_load_dwordx4 v[4:7], v172, s[14:15]
	global_load_dwordx4 v[8:11], v173, s[14:15]
	global_load_dwordx4 v[12:15], v174, s[14:15]
	global_load_dwordx4 v[16:19], v175, s[14:15]
	global_load_dwordx4 v[20:23], v177, s[14:15]
	global_load_dwordx4 v[24:27], v182, s[14:15]
	global_load_dwordx4 v[28:31], v183, s[14:15]
	s_lshl_b32 s37, s11, 8
	s_add_u32 s34, s20, s37
	s_addc_u32 s35, s21, 0
	global_load_dwordx4 v[144:147], v191, s[34:35]
	global_load_dwordx4 v[148:151], v191, s[34:35] offset:16
	s_waitcnt vmcnt(20)
	s_branch .Ltr_pr1_p3up

; #define LAS __attribute__((address_space(3)))
; __device__ __forceinline__ unsigned cvtpk(float lo, float hi) { f32x2_t v = {lo, hi}; bf16x2_t b = __builtin_convertvector(v, bf16x2_t); return __builtin_bit_cast(unsigned, b); }
; template <int MODE>
; __device__ __forceinline__ void transpose_item(const float* W, int N, bf16_t* WT, int ldt, int coff, LAS float* scr, int item, int lane, const float* g) {
;     const int nblk = N / 32, kb = item / nblk, nb = item % nblk, k0 = 64 * kb, n0 = 32 * nb;
; #pragma unroll 8
;     for (int i = 0; i < 32; ++i) { const int kk = 2 * i + (lane >> 5); float v = W[(size_t)(k0 + kk) * N + n0 + (lane & 31)]; if (MODE >= 1) v *= g[k0 + kk]; scr[kk * 33 + (lane & 31)] = v; }
;     asm volatile("s_waitcnt lgkmcnt(0)" ::: "memory");
;     const int c = lane & 7;
; #pragma unroll
;     for (int j = 0; j < 4; ++j) {
;         const int n = (lane >> 3) + 8 * j; const LAS float* s = scr + (8 * c) * 33 + n;
;         u32x4 o; o.x = cvtpk(s[0 * 33], s[1 * 33]); o.y = cvtpk(s[2 * 33], s[3 * 33]); o.z = cvtpk(s[4 * 33], s[5 * 33]); o.w = cvtpk(s[6 * 33], s[7 * 33]);
;         int dr = n0 + n;
;         if (MODE == 1) { dr = (dr < DFF) ? 256 * (dr >> 7) + (dr & 127) : 256 * ((dr - DFF) >> 7) + 128 + ((dr - DFF) & 127); }
;         if (MODE == 2) {
;             if (dr >= 6144) { const int t = dr - 6144, ch = t & 2047; dr = 6144 + 256 * (ch >> 7) + ((t >> 11) << 7) + (ch & 127); }
;             else if (dr >= 4096) { const int t = dr - 4096, ch = t & 1023; dr = 4096 + 256 * (ch >> 7) + ((t >> 10) << 7) + (ch & 127); }
;         }
;         *(u32x4*)(WT + (size_t)dr * ldt + coff + k0 + 8 * c) = o;
;     }
;     asm volatile("s_waitcnt lgkmcnt(0)" ::: "memory");
; }
.Ltr_pr1_p3up:
	s_add_u32 s9, s9, 0x400
	s_lshr_b32 s11, s10, 5
	s_mul_hi_u32 s11, s11, 0xba2e8ba3
	s_lshr_b32 s11, s11, 3
	s_mul_i32 s36, s11, 0x160
	s_sub_u32 s36, s10, s36
	s_cmp_ge_u32 s36, 0xb0
	s_cselect_b32 s37, 0xb0, 0
	s_cselect_b32 s40, 0x80, 0
	s_sub_u32 s36, s36, s37
	s_lshl_b32 s36, s36, 5
	s_and_b32 s37, s36, 0xffffff80
	s_and_b32 s36, s36, 0x7f
	s_lshl_b32 s37, s37, 1
	s_add_u32 s37, s37, s36
	s_add_u32 s37, s37, s40
	s_mul_i32 s37, s37, 0x1000
	s_lshl_b32 s11, s11, 7
	s_add_u32 s37, s37, s11
	s_add_u32 s32, s44, s37
	s_addc_u32 s33, s45, 0
	ds_write_b32 v189, v32 offset:0
	ds_write_b32 v189, v33 offset:4
	ds_write_b32 v189, v34 offset:8
	ds_write_b32 v189, v35 offset:12
	ds_write_b32 v189, v36 offset:1056
	ds_write_b32 v189, v37 offset:1060
	ds_write_b32 v189, v38 offset:1064
	ds_write_b32 v189, v39 offset:1068
	ds_write_b32 v189, v40 offset:2112
	ds_write_b32 v189, v41 offset:2116
	ds_write_b32 v189, v42 offset:2120
	ds_write_b32 v189, v43 offset:2124
	ds_write_b32 v189, v44 offset:3168
	ds_write_b32 v189, v45 offset:3172
	ds_write_b32 v189, v46 offset:3176
	ds_write_b32 v189, v47 offset:3180
	ds_write_b32 v189, v48 offset:4224
	ds_write_b32 v189, v49 offset:4228
	ds_write_b32 v189, v50 offset:4232
	ds_write_b32 v189, v51 offset:4236
	ds_write_b32 v189, v52 offset:5280
	ds_write_b32 v189, v53 offset:5284
	ds_write_b32 v189, v54 offset:5288
	ds_write_b32 v189, v55 offset:5292
	ds_write_b32 v189, v56 offset:6336
	ds_write_b32 v189, v57 offset:6340
	ds_write_b32 v189, v58 offset:6344
	ds_write_b32 v189, v59 offset:6348
	ds_write_b32 v189, v60 offset:7392
	ds_write_b32 v189, v61 offset:7396
	ds_write_b32 v189, v62 offset:7400
	ds_write_b32 v189, v63 offset:7404
	s_waitcnt lgkmcnt(0)
	ds_read2_b32 v[96:97], v190 offset0:0 offset1:8
	ds_read2_b32 v[100:101], v190 offset0:33 offset1:41
	ds_read2_b32 v[104:105], v190 offset0:66 offset1:74
	ds_read2_b32 v[108:109], v190 offset0:99 offset1:107
	ds_read2_b32 v[112:113], v190 offset0:132 offset1:140
	ds_read2_b32 v[116:117], v190 offset0:165 offset1:173
	ds_read2_b32 v[120:121], v190 offset0:198 offset1:206
	ds_read2_b32 v[124:125], v190 offset0:231 offset1:239
	ds_read2_b32 v[98:99], v190 offset0:16 offset1:24
	ds_read2_b32 v[102:103], v190 offset0:49 offset1:57
	ds_read2_b32 v[106:107], v190 offset0:82 offset1:90
	ds_read2_b32 v[110:111], v190 offset0:115 offset1:123
	ds_read2_b32 v[114:115], v190 offset0:148 offset1:156
	ds_read2_b32 v[118:119], v190 offset0:181 offset1:189
	ds_read2_b32 v[122:123], v190 offset0:214 offset1:222
	ds_read2_b32 v[126:127], v190 offset0:247 offset1:255
	s_waitcnt lgkmcnt(0)
	v_mul_f32_e32 v96, v152, v96
	v_mul_f32_e32 v97, v152, v97
	v_mul_f32_e32 v98, v152, v98
	v_mul_f32_e32 v99, v152, v99
	v_mul_f32_e32 v100, v153, v100
	v_mul_f32_e32 v101, v153, v101
	v_mul_f32_e32 v102, v153, v102
	v_mul_f32_e32 v103, v153, v103
	v_mul_f32_e32 v104, v154, v104
	v_mul_f32_e32 v105, v154, v105
	v_mul_f32_e32 v106, v154, v106
	v_mul_f32_e32 v107, v154, v107
	v_mul_f32_e32 v108, v155, v108
	v_mul_f32_e32 v109, v155, v109
	v_mul_f32_e32 v110, v155, v110
	v_mul_f32_e32 v111, v155, v111
	v_mul_f32_e32 v112, v156, v112
	v_mul_f32_e32 v113, v156, v113
	v_mul_f32_e32 v114, v156, v114
	v_mul_f32_e32 v115, v156, v115
	v_mul_f32_e32 v116, v157, v116
	v_mul_f32_e32 v117, v157, v117
	v_mul_f32_e32 v118, v157, v118
	v_mul_f32_e32 v119, v157, v119
	v_mul_f32_e32 v120, v158, v120
	v_mul_f32_e32 v121, v158, v121
	v_mul_f32_e32 v122, v158, v122
	v_mul_f32_e32 v123, v158, v123
	v_mul_f32_e32 v124, v159, v124
	v_mul_f32_e32 v125, v159, v125
	v_mul_f32_e32 v126, v159, v126
	v_mul_f32_e32 v127, v159, v127
	v_cvt_pk_bf16_f32 v128, v96, v100
	v_cvt_pk_bf16_f32 v129, v104, v108
	v_cvt_pk_bf16_f32 v130, v112, v116
	v_cvt_pk_bf16_f32 v131, v120, v124
	global_store_dwordx4 v184, v[128:131], s[32:33]
	v_cvt_pk_bf16_f32 v132, v97, v101
	v_cvt_pk_bf16_f32 v133, v105, v109
	v_cvt_pk_bf16_f32 v134, v113, v117
	v_cvt_pk_bf16_f32 v135, v121, v125
	global_store_dwordx4 v185, v[132:135], s[32:33]
	v_cvt_pk_bf16_f32 v136, v98, v102
	v_cvt_pk_bf16_f32 v137, v106, v110
	v_cvt_pk_bf16_f32 v138, v114, v118
	v_cvt_pk_bf16_f32 v139, v122, v126
	global_store_dwordx4 v186, v[136:139], s[32:33]
	v_cvt_pk_bf16_f32 v140, v99, v103
	v_cvt_pk_bf16_f32 v141, v107, v111
	v_cvt_pk_bf16_f32 v142, v115, v119
	v_cvt_pk_bf16_f32 v143, v123, v127
	global_store_dwordx4 v188, v[140:143], s[32:33]
	s_add_u32 s10, s10, 0x400
	s_cmp_lt_u32 s10, 0x2c00
	s_cbranch_scc0 .Ltr_done_p3up
.Ltr_st2_p3up:
	s_cmp_lt_u32 s9, 0x2c00
	s_cbranch_scc0 .Ltr_nl2_p3up
	s_lshr_b32 s11, s9, 5
	s_mul_hi_u32 s11, s11, 0xba2e8ba3
	s_lshr_b32 s11, s11, 3
	s_mul_i32 s36, s11, 0x160
	s_sub_u32 s36, s9, s36
	s_mul_i32 s37, s11, 0x2c0000
	s_lshl_b32 s36, s36, 7
	s_add_u32 s37, s37, s36
	s_add_u32 s14, s22, s37
	s_addc_u32 s15, s23, 0
	global_load_dwordx4 v[32:35], v171, s[14:15]
	global_load_dwordx4 v[36:39], v172, s[14:15]
	global_load_dwordx4 v[40:43], v173, s[14:15]
	global_load_dwordx4 v[44:47], v174, s[14:15]
	global_load_dwordx4 v[48:51], v175, s[14:15]
	global_load_dwordx4 v[52:55], v177, s[14:15]
	global_load_dwordx4 v[56:59], v182, s[14:15]
	global_load_dwordx4 v[60:63], v183, s[14:15]
	s_lshl_b32 s37, s11, 8
	s_add_u32 s34, s20, s37
	s_addc_u32 s35, s21, 0
	global_load_dwordx4 v[152:155], v191, s[34:35]
	global_load_dwordx4 v[156:159], v191, s[34:35] offset:16
	s_waitcnt vmcnt(20)
	s_branch .Ltr_pr2_p3up

; #define LAS __attribute__((address_space(3)))
; __device__ __forceinline__ unsigned cvtpk(float lo, float hi) { f32x2_t v = {lo, hi}; bf16x2_t b = __builtin_convertvector(v, bf16x2_t); return __builtin_bit_cast(unsigned, b); }
; template <int MODE>
; __device__ __forceinline__ void transpose_item(const float* W, int N, bf16_t* WT, int ldt, int coff, LAS float* scr, int item, int lane, const float* g) {
;     const int nblk = N / 32, kb = item / nblk, nb = item % nblk, k0 = 64 * kb, n0 = 32 * nb;
; #pragma unroll 8
;     for (int i = 0; i < 32; ++i) { const int kk = 2 * i + (lane >> 5); float v = W[(size_t)(k0 + kk) * N + n0 + (lane & 31)]; if (MODE >= 1) v *= g[k0 + kk]; scr[kk * 33 + (lane & 31)] = v; }
;     asm volatile("s_waitcnt lgkmcnt(0)" ::: "memory");
;     const int c = lane & 7;
; #pragma unroll
;     for (int j = 0; j < 4; ++j) {
;         const int n = (lane >> 3) + 8 * j; const LAS float* s = scr + (8 * c) * 33 + n;
;         u32x4 o; o.x = cvtpk(s[0 * 33], s[1 * 33]); o.y = cvtpk(s[2 * 33], s[3 * 33]); o.z = cvtpk(s[4 * 33], s[5 * 33]); o.w = cvtpk(s[6 * 33], s[7 * 33]);
;         int dr = n0 + n;
;         if (MODE == 1) { dr = (dr < DFF) ? 256 * (dr >> 7) + (dr & 127) : 256 * ((dr - DFF) >> 7) + 128 + ((dr - DFF) & 127); }
;         if (MODE == 2) {
;             if (dr >= 6144) { const int t = dr - 6144, ch = t & 2047; dr = 6144 + 256 * (ch >> 7) + ((t >> 11) << 7) + (ch & 127); }
;             else if (dr >= 4096) { const int t = dr - 4096, ch = t & 1023; dr = 4096 + 256 * (ch >> 7) + ((t >> 10) << 7) + (ch & 127); }
;         }
;         *(u32x4*)(WT + (size_t)dr * ldt + coff + k0 + 8 * c) = o;
;     }
;     asm volatile("s_waitcnt lgkmcnt(0)" ::: "memory");
; }
; __global__ void __launch_bounds__(512, 2) mk_fwd(Args a) {
;     ...
;         for (int it = gw; it < I_U + I_D; it += NGW) {
;             if (it < I_U) transpose_item<1>(a.in[I_WUP], 2 * DFF, WUP, DM, 0, scr, it, lane, a.in[I_N2]);
;             else transpose_item<0>(a.in[I_WDN], DM, WDN, DFF, 0, scr, it - I_U, lane, nullptr);
;         }
.Ltr_pr2_p3up:
	s_add_u32 s9, s9, 0x400
	s_lshr_b32 s11, s10, 5
	s_mul_hi_u32 s11, s11, 0xba2e8ba3
	s_lshr_b32 s11, s11, 3
	s_mul_i32 s36, s11, 0x160
	s_sub_u32 s36, s10, s36
	s_cmp_ge_u32 s36, 0xb0
	s_cselect_b32 s37, 0xb0, 0
	s_cselect_b32 s40, 0x80, 0
	s_sub_u32 s36, s36, s37
	s_lshl_b32 s36, s36, 5
	s_and_b32 s37, s36, 0xffffff80
	s_and_b32 s36, s36, 0x7f
	s_lshl_b32 s37, s37, 1
	s_add_u32 s37, s37, s36
	s_add_u32 s37, s37, s40
	s_mul_i32 s37, s37, 0x1000
	s_lshl_b32 s11, s11, 7
	s_add_u32 s37, s37, s11
	s_add_u32 s32, s44, s37
	s_addc_u32 s33, s45, 0
	ds_write_b32 v189, v64 offset:0
	ds_write_b32 v189, v65 offset:4
	ds_write_b32 v189, v66 offset:8
	ds_write_b32 v189, v67 offset:12
	ds_write_b32 v189, v68 offset:1056
	ds_write_b32 v189, v69 offset:1060
	ds_write_b32 v189, v70 offset:1064
	ds_write_b32 v189, v71 offset:1068
	ds_write_b32 v189, v72 offset:2112
	ds_write_b32 v189, v73 offset:2116
	ds_write_b32 v189, v74 offset:2120
	ds_write_b32 v189, v75 offset:2124
	ds_write_b32 v189, v76 offset:3168
	ds_write_b32 v189, v77 offset:3172
	ds_write_b32 v189, v78 offset:3176
	ds_write_b32 v189, v79 offset:3180
	ds_write_b32 v189, v80 offset:4224
	ds_write_b32 v189, v81 offset:4228
	ds_write_b32 v189, v82 offset:4232
	ds_write_b32 v189, v83 offset:4236
	ds_write_b32 v189, v84 offset:5280
	ds_write_b32 v189, v85 offset:5284
	ds_write_b32 v189, v86 offset:5288
	ds_write_b32 v189, v87 offset:5292
	ds_write_b32 v189, v88 offset:6336
	ds_write_b32 v189, v89 offset:6340
	ds_write_b32 v189, v90 offset:6344
	ds_write_b32 v189, v91 offset:6348
	ds_write_b32 v189, v92 offset:7392
	ds_write_b32 v189, v93 offset:7396
	ds_write_b32 v189, v94 offset:7400
	ds_write_b32 v189, v95 offset:7404
	s_waitcnt lgkmcnt(0)
	ds_read2_b32 v[96:97], v190 offset0:0 offset1:8
	ds_read2_b32 v[100:101], v190 offset0:33 offset1:41
	ds_read2_b32 v[104:105], v190 offset0:66 offset1:74
	ds_read2_b32 v[108:109], v190 offset0:99 offset1:107
	ds_read2_b32 v[112:113], v190 offset0:132 offset1:140
	ds_read2_b32 v[116:117], v190 offset0:165 offset1:173
	ds_read2_b32 v[120:121], v190 offset0:198 offset1:206
	ds_read2_b32 v[124:125], v190 offset0:231 offset1:239
	ds_read2_b32 v[98:99], v190 offset0:16 offset1:24
	ds_read2_b32 v[102:103], v190 offset0:49 offset1:57
	ds_read2_b32 v[106:107], v190 offset0:82 offset1:90
	ds_read2_b32 v[110:111], v190 offset0:115 offset1:123
	ds_read2_b32 v[114:115], v190 offset0:148 offset1:156
	ds_read2_b32 v[118:119], v190 offset0:181 offset1:189
	ds_read2_b32 v[122:123], v190 offset0:214 offset1:222
	ds_read2_b32 v[126:127], v190 offset0:247 offset1:255
	s_waitcnt lgkmcnt(0)
	v_mul_f32_e32 v96, v160, v96
	v_mul_f32_e32 v97, v160, v97
	v_mul_f32_e32 v98, v160, v98
	v_mul_f32_e32 v99, v160, v99
	v_mul_f32_e32 v100, v161, v100
	v_mul_f32_e32 v101, v161, v101
	v_mul_f32_e32 v102, v161, v102
	v_mul_f32_e32 v103, v161, v103
	v_mul_f32_e32 v104, v162, v104
	v_mul_f32_e32 v105, v162, v105
	v_mul_f32_e32 v106, v162, v106
	v_mul_f32_e32 v107, v162, v107
	v_mul_f32_e32 v108, v163, v108
	v_mul_f32_e32 v109, v163, v109
	v_mul_f32_e32 v110, v163, v110
	v_mul_f32_e32 v111, v163, v111
	v_mul_f32_e32 v112, v164, v112
	v_mul_f32_e32 v113, v164, v113
	v_mul_f32_e32 v114, v164, v114
	v_mul_f32_e32 v115, v164, v115
	v_mul_f32_e32 v116, v165, v116
	v_mul_f32_e32 v117, v165, v117
	v_mul_f32_e32 v118, v165, v118
	v_mul_f32_e32 v119, v165, v119
	v_mul_f32_e32 v120, v166, v120
	v_mul_f32_e32 v121, v166, v121
	v_mul_f32_e32 v122, v166, v122
	v_mul_f32_e32 v123, v166, v123
	v_mul_f32_e32 v124, v167, v124
	v_mul_f32_e32 v125, v167, v125
	v_mul_f32_e32 v126, v167, v126
	v_mul_f32_e32 v127, v167, v127
	v_cvt_pk_bf16_f32 v128, v96, v100
	v_cvt_pk_bf16_f32 v129, v104, v108
	v_cvt_pk_bf16_f32 v130, v112, v116
	v_cvt_pk_bf16_f32 v131, v120, v124
	global_store_dwordx4 v184, v[128:131], s[32:33]
	v_cvt_pk_bf16_f32 v132, v97, v101
	v_cvt_pk_bf16_f32 v133, v105, v109
	v_cvt_pk_bf16_f32 v134, v113, v117
	v_cvt_pk_bf16_f32 v135, v121, v125
	global_store_dwordx4 v185, v[132:135], s[32:33]
	v_cvt_pk_bf16_f32 v136, v98, v102
	v_cvt_pk_bf16_f32 v137, v106, v110
	v_cvt_pk_bf16_f32 v138, v114, v118
	v_cvt_pk_bf16_f32 v139, v122, v126
	global_store_dwordx4 v186, v[136:139], s[32:33]
	v_cvt_pk_bf16_f32 v140, v99, v103
	v_cvt_pk_bf16_f32 v141, v107, v111
	v_cvt_pk_bf16_f32 v142, v115, v119
	v_cvt_pk_bf16_f32 v143, v123, v127
	global_store_dwordx4 v188, v[140:143], s[32:33]
	s_add_u32 s10, s10, 0x400
	s_cmp_lt_u32 s10, 0x2c00
	s_cbranch_scc0 .Ltr_done_p3up
	s_branch .Ltr_st0_p3up
.Ltr_done_p3up:
	s_cmp_lt_u32 s1, 0x1600
	s_cbranch_scc0 .Ltr_done_p3dn
	v_lshrrev_b32_e32 v144, 3, v220
	v_and_b32_e32 v145, 7, v220
	v_mul_u32_u24_e32 v146, 0x2000, v144
	v_lshl_add_u32 v147, v145, 4, v146
	v_add_u32_e32 v148, 0x10000, v147
	v_add_u32_e32 v149, 0x20000, v147
	v_add_u32_e32 v150, 0x30000, v147
	v_add_u32_e32 v151, 0x40000, v147
	v_add_u32_e32 v152, 0x50000, v147
	v_add_u32_e32 v153, 0x60000, v147
	v_add_u32_e32 v154, 0x70000, v147
	v_mul_u32_u24_e32 v146, 0x84, v144
	v_lshl_add_u32 v146, v145, 4, v146
	v_add_u32_e32 v159, s0, v146
	v_mul_u32_u24_e32 v146, 0x420, v145
	v_lshl_add_u32 v146, v144, 2, v146
	v_add_u32_e32 v160, s0, v146
	v_mul_u32_u24_e32 v146, 0x2c00, v144
	v_lshl_add_u32 v155, v145, 4, v146
	v_add_u32_e32 v156, 0x16000, v155
	v_add_u32_e32 v157, 0x2c000, v155
	v_add_u32_e32 v158, 0x42000, v155
	s_mov_b32 s10, s1
	s_mov_b32 s9, s1
	s_lshr_b32 s11, s9, 6
	s_and_b32 s34, s9, 0x3f
	s_mul_i32 s35, s11, 0x80000
	s_lshl_b32 s34, s34, 7
	s_add_u32 s35, s35, s34
	s_add_u32 s14, s26, s35
	s_addc_u32 s15, s27, 0
	global_load_dwordx4 v[0:3], v147, s[14:15]
	global_load_dwordx4 v[4:7], v148, s[14:15]
	global_load_dwordx4 v[8:11], v149, s[14:15]
	global_load_dwordx4 v[12:15], v150, s[14:15]
	global_load_dwordx4 v[16:19], v151, s[14:15]
	global_load_dwordx4 v[20:23], v152, s[14:15]
	global_load_dwordx4 v[24:27], v153, s[14:15]
	global_load_dwordx4 v[28:31], v154, s[14:15]
	s_add_u32 s9, s9, 0x400
	s_cmp_lt_u32 s9, 0x1600
	s_cbranch_scc0 .Ltr_p1_p3dn
	s_lshr_b32 s11, s9, 6
	s_and_b32 s34, s9, 0x3f
	s_mul_i32 s35, s11, 0x80000
	s_lshl_b32 s34, s34, 7
	s_add_u32 s35, s35, s34
	s_add_u32 s14, s26, s35
	s_addc_u32 s15, s27, 0
	global_load_dwordx4 v[32:35], v147, s[14:15]
	global_load_dwordx4 v[36:39], v148, s[14:15]
	global_load_dwordx4 v[40:43], v149, s[14:15]
	global_load_dwordx4 v[44:47], v150, s[14:15]
	global_load_dwordx4 v[48:51], v151, s[14:15]
	global_load_dwordx4 v[52:55], v152, s[14:15]
	global_load_dwordx4 v[56:59], v153, s[14:15]
	global_load_dwordx4 v[60:63], v154, s[14:15]

; #define LAS __attribute__((address_space(3)))
; template <int MODE>
; __device__ __forceinline__ void transpose_item(const float* W, int N, bf16_t* WT, int ldt, int coff, LAS float* scr, int item, int lane, const float* g) {
;     const int nblk = N / 32, kb = item / nblk, nb = item % nblk, k0 = 64 * kb, n0 = 32 * nb;
; #pragma unroll 8
;     for (int i = 0; i < 32; ++i) { const int kk = 2 * i + (lane >> 5); float v = W[(size_t)(k0 + kk) * N + n0 + (lane & 31)]; if (MODE >= 1) v *= g[k0 + kk]; scr[kk * 33 + (lane & 31)] = v; }
.Ltr_st0_p3dn:
	s_cmp_lt_u32 s9, 0x1600
	s_cbranch_scc0 .Ltr_nl0_p3dn
	s_lshr_b32 s11, s9, 6
	s_and_b32 s34, s9, 0x3f
	s_mul_i32 s35, s11, 0x80000
	s_lshl_b32 s34, s34, 7
	s_add_u32 s35, s35, s34
	s_add_u32 s14, s26, s35
	s_addc_u32 s15, s27, 0
	global_load_dwordx4 v[64:67], v147, s[14:15]
	global_load_dwordx4 v[68:71], v148, s[14:15]
	global_load_dwordx4 v[72:75], v149, s[14:15]
	global_load_dwordx4 v[76:79], v150, s[14:15]
	global_load_dwordx4 v[80:83], v151, s[14:15]
	global_load_dwordx4 v[84:87], v152, s[14:15]
	global_load_dwordx4 v[88:91], v153, s[14:15]
	global_load_dwordx4 v[92:95], v154, s[14:15]
	s_waitcnt vmcnt(16)
	s_branch .Ltr_pr0_p3dn
.Ltr_nl0_p3dn:
	s_sub_u32 s11, s9, 0x400
	s_cmp_lt_u32 s11, 0x1600
	s_cbranch_scc0 .Ltr_w00_p3dn
	s_waitcnt vmcnt(8)
	s_branch .Ltr_pr0_p3dn

; #define LAS __attribute__((address_space(3)))
; __device__ __forceinline__ unsigned cvtpk(float lo, float hi) { f32x2_t v = {lo, hi}; bf16x2_t b = __builtin_convertvector(v, bf16x2_t); return __builtin_bit_cast(unsigned, b); }
; template <int MODE>
; __device__ __forceinline__ void transpose_item(const float* W, int N, bf16_t* WT, int ldt, int coff, LAS float* scr, int item, int lane, const float* g) {
;     ...
;     for (int i = 0; i < 32; ++i) { const int kk = 2 * i + (lane >> 5); float v = W[(size_t)(k0 + kk) * N + n0 + (lane & 31)]; if (MODE >= 1) v *= g[k0 + kk]; scr[kk * 33 + (lane & 31)] = v; }
;     asm volatile("s_waitcnt lgkmcnt(0)" ::: "memory");
;     const int c = lane & 7;
; #pragma unroll
;     for (int j = 0; j < 4; ++j) {
;         const int n = (lane >> 3) + 8 * j; const LAS float* s = scr + (8 * c) * 33 + n;
;         u32x4 o; o.x = cvtpk(s[0 * 33], s[1 * 33]); o.y = cvtpk(s[2 * 33], s[3 * 33]); o.z = cvtpk(s[4 * 33], s[5 * 33]); o.w = cvtpk(s[6 * 33], s[7 * 33]);
;         int dr = n0 + n;
;         if (MODE == 1) { dr = (dr < DFF) ? 256 * (dr >> 7) + (dr & 127) : 256 * ((dr - DFF) >> 7) + 128 + ((dr - DFF) & 127); }
;         if (MODE == 2) {
;             if (dr >= 6144) { const int t = dr - 6144, ch = t & 2047; dr = 6144 + 256 * (ch >> 7) + ((t >> 11) << 7) + (ch & 127); }
;             else if (dr >= 4096) { const int t = dr - 4096, ch = t & 1023; dr = 4096 + 256 * (ch >> 7) + ((t >> 10) << 7) + (ch & 127); }
;         }
;         *(u32x4*)(WT + (size_t)dr * ldt + coff + k0 + 8 * c) = o;
;     }
;     asm volatile("s_waitcnt lgkmcnt(0)" ::: "memory");
.Ltr_pr0_p3dn:
	s_add_u32 s9, s9, 0x400
	s_lshr_b32 s11, s10, 6
	s_and_b32 s34, s10, 0x3f
	s_mul_i32 s35, s34, 0x58000
	s_lshl_b32 s11, s11, 7
	s_add_u32 s35, s35, s11
	s_add_u32 s32, s6, s35
	s_addc_u32 s33, s7, 0
	ds_write_b32 v159, v0 offset:0
	ds_write_b32 v159, v1 offset:4
	ds_write_b32 v159, v2 offset:8
	ds_write_b32 v159, v3 offset:12
	ds_write_b32 v159, v4 offset:1056
	ds_write_b32 v159, v5 offset:1060
	ds_write_b32 v159, v6 offset:1064
	ds_write_b32 v159, v7 offset:1068
	ds_write_b32 v159, v8 offset:2112
	ds_write_b32 v159, v9 offset:2116
	ds_write_b32 v159, v10 offset:2120
	ds_write_b32 v159, v11 offset:2124
	ds_write_b32 v159, v12 offset:3168
	ds_write_b32 v159, v13 offset:3172
	ds_write_b32 v159, v14 offset:3176
	ds_write_b32 v159, v15 offset:3180
	ds_write_b32 v159, v16 offset:4224
	ds_write_b32 v159, v17 offset:4228
	ds_write_b32 v159, v18 offset:4232
	ds_write_b32 v159, v19 offset:4236
	ds_write_b32 v159, v20 offset:5280
	ds_write_b32 v159, v21 offset:5284
	ds_write_b32 v159, v22 offset:5288
	ds_write_b32 v159, v23 offset:5292
	ds_write_b32 v159, v24 offset:6336
	ds_write_b32 v159, v25 offset:6340
	ds_write_b32 v159, v26 offset:6344
	ds_write_b32 v159, v27 offset:6348
	ds_write_b32 v159, v28 offset:7392
	ds_write_b32 v159, v29 offset:7396
	ds_write_b32 v159, v30 offset:7400
	ds_write_b32 v159, v31 offset:7404
	s_waitcnt lgkmcnt(0)
	ds_read2_b32 v[96:97], v160 offset0:0 offset1:8
	ds_read2_b32 v[100:101], v160 offset0:33 offset1:41
	ds_read2_b32 v[104:105], v160 offset0:66 offset1:74
	ds_read2_b32 v[108:109], v160 offset0:99 offset1:107
	ds_read2_b32 v[112:113], v160 offset0:132 offset1:140
	ds_read2_b32 v[116:117], v160 offset0:165 offset1:173
	ds_read2_b32 v[120:121], v160 offset0:198 offset1:206
	ds_read2_b32 v[124:125], v160 offset0:231 offset1:239
	ds_read2_b32 v[98:99], v160 offset0:16 offset1:24
	ds_read2_b32 v[102:103], v160 offset0:49 offset1:57
	ds_read2_b32 v[106:107], v160 offset0:82 offset1:90
	ds_read2_b32 v[110:111], v160 offset0:115 offset1:123
	ds_read2_b32 v[114:115], v160 offset0:148 offset1:156
	ds_read2_b32 v[118:119], v160 offset0:181 offset1:189
	ds_read2_b32 v[122:123], v160 offset0:214 offset1:222
	ds_read2_b32 v[126:127], v160 offset0:247 offset1:255
	s_waitcnt lgkmcnt(0)
	v_cvt_pk_bf16_f32 v128, v96, v100
	v_cvt_pk_bf16_f32 v129, v104, v108
	v_cvt_pk_bf16_f32 v130, v112, v116
	v_cvt_pk_bf16_f32 v131, v120, v124
	global_store_dwordx4 v155, v[128:131], s[32:33]
	v_cvt_pk_bf16_f32 v132, v97, v101
	v_cvt_pk_bf16_f32 v133, v105, v109
	v_cvt_pk_bf16_f32 v134, v113, v117
	v_cvt_pk_bf16_f32 v135, v121, v125
	global_store_dwordx4 v156, v[132:135], s[32:33]
	v_cvt_pk_bf16_f32 v136, v98, v102
	v_cvt_pk_bf16_f32 v137, v106, v110
	v_cvt_pk_bf16_f32 v138, v114, v118
	v_cvt_pk_bf16_f32 v139, v122, v126
	global_store_dwordx4 v157, v[136:139], s[32:33]
	v_cvt_pk_bf16_f32 v140, v99, v103
	v_cvt_pk_bf16_f32 v141, v107, v111
	v_cvt_pk_bf16_f32 v142, v115, v119
	v_cvt_pk_bf16_f32 v143, v123, v127
	global_store_dwordx4 v158, v[140:143], s[32:33]
	s_add_u32 s10, s10, 0x400
	s_cmp_lt_u32 s10, 0x1600
	s_cbranch_scc0 .Ltr_done_p3dn
.Ltr_st1_p3dn:
	s_cmp_lt_u32 s9, 0x1600
	s_cbranch_scc0 .Ltr_nl1_p3dn
	s_lshr_b32 s11, s9, 6
	s_and_b32 s34, s9, 0x3f
	s_mul_i32 s35, s11, 0x80000
	s_lshl_b32 s34, s34, 7
	s_add_u32 s35, s35, s34
	s_add_u32 s14, s26, s35
	s_addc_u32 s15, s27, 0
	global_load_dwordx4 v[0:3], v147, s[14:15]
	global_load_dwordx4 v[4:7], v148, s[14:15]
	global_load_dwordx4 v[8:11], v149, s[14:15]
	global_load_dwordx4 v[12:15], v150, s[14:15]
	global_load_dwordx4 v[16:19], v151, s[14:15]
	global_load_dwordx4 v[20:23], v152, s[14:15]
	global_load_dwordx4 v[24:27], v153, s[14:15]
	global_load_dwordx4 v[28:31], v154, s[14:15]
	s_waitcnt vmcnt(16)
	s_branch .Ltr_pr1_p3dn

; #define LAS __attribute__((address_space(3)))
; __device__ __forceinline__ unsigned cvtpk(float lo, float hi) { f32x2_t v = {lo, hi}; bf16x2_t b = __builtin_convertvector(v, bf16x2_t); return __builtin_bit_cast(unsigned, b); }
; template <int MODE>
; __device__ __forceinline__ void transpose_item(const float* W, int N, bf16_t* WT, int ldt, int coff, LAS float* scr, int item, int lane, const float* g) {
;     ...
;     for (int i = 0; i < 32; ++i) { const int kk = 2 * i + (lane >> 5); float v = W[(size_t)(k0 + kk) * N + n0 + (lane & 31)]; if (MODE >= 1) v *= g[k0 + kk]; scr[kk * 33 + (lane & 31)] = v; }
;     asm volatile("s_waitcnt lgkmcnt(0)" ::: "memory");
;     const int c = lane & 7;
; #pragma unroll
;     for (int j = 0; j < 4; ++j) {
;         const int n = (lane >> 3) + 8 * j; const LAS float* s = scr + (8 * c) * 33 + n;
;         u32x4 o; o.x = cvtpk(s[0 * 33], s[1 * 33]); o.y = cvtpk(s[2 * 33], s[3 * 33]); o.z = cvtpk(s[4 * 33], s[5 * 33]); o.w = cvtpk(s[6 * 33], s[7 * 33]);
;         int dr = n0 + n;
;         if (MODE == 1) { dr = (dr < DFF) ? 256 * (dr >> 7) + (dr & 127) : 256 * ((dr - DFF) >> 7) + 128 + ((dr - DFF) & 127); }
;         if (MODE == 2) {
;             if (dr >= 6144) { const int t = dr - 6144, ch = t & 2047; dr = 6144 + 256 * (ch >> 7) + ((t >> 11) << 7) + (ch & 127); }
;             else if (dr >= 4096) { const int t = dr - 4096, ch = t & 1023; dr = 4096 + 256 * (ch >> 7) + ((t >> 10) << 7) + (ch & 127); }
;         }
;         *(u32x4*)(WT + (size_t)dr * ldt + coff + k0 + 8 * c) = o;
;     }
;     asm volatile("s_waitcnt lgkmcnt(0)" ::: "memory");
.Ltr_pr1_p3dn:
	s_add_u32 s9, s9, 0x400
	s_lshr_b32 s11, s10, 6
	s_and_b32 s34, s10, 0x3f
	s_mul_i32 s35, s34, 0x58000
	s_lshl_b32 s11, s11, 7
	s_add_u32 s35, s35, s11
	s_add_u32 s32, s6, s35
	s_addc_u32 s33, s7, 0
	ds_write_b32 v159, v32 offset:0
	ds_write_b32 v159, v33 offset:4
	ds_write_b32 v159, v34 offset:8
	ds_write_b32 v159, v35 offset:12
	ds_write_b32 v159, v36 offset:1056
	ds_write_b32 v159, v37 offset:1060
	ds_write_b32 v159, v38 offset:1064
	ds_write_b32 v159, v39 offset:1068
	ds_write_b32 v159, v40 offset:2112
	ds_write_b32 v159, v41 offset:2116
	ds_write_b32 v159, v42 offset:2120
	ds_write_b32 v159, v43 offset:2124
	ds_write_b32 v159, v44 offset:3168
	ds_write_b32 v159, v45 offset:3172
	ds_write_b32 v159, v46 offset:3176
	ds_write_b32 v159, v47 offset:3180
	ds_write_b32 v159, v48 offset:4224
	ds_write_b32 v159, v49 offset:4228
	ds_write_b32 v159, v50 offset:4232
	ds_write_b32 v159, v51 offset:4236
	ds_write_b32 v159, v52 offset:5280
	ds_write_b32 v159, v53 offset:5284
	ds_write_b32 v159, v54 offset:5288
	ds_write_b32 v159, v55 offset:5292
	ds_write_b32 v159, v56 offset:6336
	ds_write_b32 v159, v57 offset:6340
	ds_write_b32 v159, v58 offset:6344
	ds_write_b32 v159, v59 offset:6348
	ds_write_b32 v159, v60 offset:7392
	ds_write_b32 v159, v61 offset:7396
	ds_write_b32 v159, v62 offset:7400
	ds_write_b32 v159, v63 offset:7404
	s_waitcnt lgkmcnt(0)
	ds_read2_b32 v[96:97], v160 offset0:0 offset1:8
	ds_read2_b32 v[100:101], v160 offset0:33 offset1:41
	ds_read2_b32 v[104:105], v160 offset0:66 offset1:74
	ds_read2_b32 v[108:109], v160 offset0:99 offset1:107
	ds_read2_b32 v[112:113], v160 offset0:132 offset1:140
	ds_read2_b32 v[116:117], v160 offset0:165 offset1:173
	ds_read2_b32 v[120:121], v160 offset0:198 offset1:206
	ds_read2_b32 v[124:125], v160 offset0:231 offset1:239
	ds_read2_b32 v[98:99], v160 offset0:16 offset1:24
	ds_read2_b32 v[102:103], v160 offset0:49 offset1:57
	ds_read2_b32 v[106:107], v160 offset0:82 offset1:90
	ds_read2_b32 v[110:111], v160 offset0:115 offset1:123
	ds_read2_b32 v[114:115], v160 offset0:148 offset1:156
	ds_read2_b32 v[118:119], v160 offset0:181 offset1:189
	ds_read2_b32 v[122:123], v160 offset0:214 offset1:222
	ds_read2_b32 v[126:127], v160 offset0:247 offset1:255
	s_waitcnt lgkmcnt(0)
	v_cvt_pk_bf16_f32 v128, v96, v100
	v_cvt_pk_bf16_f32 v129, v104, v108
	v_cvt_pk_bf16_f32 v130, v112, v116
	v_cvt_pk_bf16_f32 v131, v120, v124
	global_store_dwordx4 v155, v[128:131], s[32:33]
	v_cvt_pk_bf16_f32 v132, v97, v101
	v_cvt_pk_bf16_f32 v133, v105, v109
	v_cvt_pk_bf16_f32 v134, v113, v117
	v_cvt_pk_bf16_f32 v135, v121, v125
	global_store_dwordx4 v156, v[132:135], s[32:33]
	v_cvt_pk_bf16_f32 v136, v98, v102
	v_cvt_pk_bf16_f32 v137, v106, v110
	v_cvt_pk_bf16_f32 v138, v114, v118
	v_cvt_pk_bf16_f32 v139, v122, v126
	global_store_dwordx4 v157, v[136:139], s[32:33]
	v_cvt_pk_bf16_f32 v140, v99, v103
	v_cvt_pk_bf16_f32 v141, v107, v111
	v_cvt_pk_bf16_f32 v142, v115, v119
	v_cvt_pk_bf16_f32 v143, v123, v127
	global_store_dwordx4 v158, v[140:143], s[32:33]
	s_add_u32 s10, s10, 0x400
	s_cmp_lt_u32 s10, 0x1600
	s_cbranch_scc0 .Ltr_done_p3dn
.Ltr_st2_p3dn:
	s_cmp_lt_u32 s9, 0x1600
	s_cbranch_scc0 .Ltr_nl2_p3dn
	s_lshr_b32 s11, s9, 6
	s_and_b32 s34, s9, 0x3f
	s_mul_i32 s35, s11, 0x80000
	s_lshl_b32 s34, s34, 7
	s_add_u32 s35, s35, s34
	s_add_u32 s14, s26, s35
	s_addc_u32 s15, s27, 0
	global_load_dwordx4 v[32:35], v147, s[14:15]
	global_load_dwordx4 v[36:39], v148, s[14:15]
	global_load_dwordx4 v[40:43], v149, s[14:15]
	global_load_dwordx4 v[44:47], v150, s[14:15]
	global_load_dwordx4 v[48:51], v151, s[14:15]
	global_load_dwordx4 v[52:55], v152, s[14:15]
	global_load_dwordx4 v[56:59], v153, s[14:15]
	global_load_dwordx4 v[60:63], v154, s[14:15]
	s_waitcnt vmcnt(16)
	s_branch .Ltr_pr2_p3dn

; #define LAS __attribute__((address_space(3)))
; __device__ __forceinline__ unsigned cvtpk(float lo, float hi) { f32x2_t v = {lo, hi}; bf16x2_t b = __builtin_convertvector(v, bf16x2_t); return __builtin_bit_cast(unsigned, b); }
; template <class Epi>
; __device__ __forceinline__ void gemm_quarter(LAS unsigned char* lds, const Gemm g, const Unit u, const Epi& E) {
;     ...
;     unsigned voffA[2], voffB[2];
; #pragma unroll
;     for (int i = 0; i < 2; ++i) { int R, C; stage_rc(tid * 16 + i * 8192, R, C); const int Rb = (R & ~31) + perm32(R & 31);
;         voffA[i] = (unsigned)(R * g.lda + C) * 2u; voffB[i] = (unsigned)(Rb * g.ldb + C) * 2u; }
;     const unsigned ldsw = (unsigned)wid * 1024u;
;     const int aoff = lds_byte(wr * 64 + fr, fq * 8), boff = lds_byte(wc * 32 + fr, fq * 8);
; template <int MODE>
; __device__ __forceinline__ void transpose_item(const float* W, int N, bf16_t* WT, int ldt, int coff, LAS float* scr, int item, int lane, const float* g) {
;     ...
;     for (int i = 0; i < 32; ++i) { const int kk = 2 * i + (lane >> 5); float v = W[(size_t)(k0 + kk) * N + n0 + (lane & 31)]; if (MODE >= 1) v *= g[k0 + kk]; scr[kk * 33 + (lane & 31)] = v; }
;     asm volatile("s_waitcnt lgkmcnt(0)" ::: "memory");
;     const int c = lane & 7;
; #pragma unroll
;     for (int j = 0; j < 4; ++j) {
;         const int n = (lane >> 3) + 8 * j; const LAS float* s = scr + (8 * c) * 33 + n;
;         u32x4 o; o.x = cvtpk(s[0 * 33], s[1 * 33]); o.y = cvtpk(s[2 * 33], s[3 * 33]); o.z = cvtpk(s[4 * 33], s[5 * 33]); o.w = cvtpk(s[6 * 33], s[7 * 33]);
;         int dr = n0 + n;
;         if (MODE == 1) { dr = (dr < DFF) ? 256 * (dr >> 7) + (dr & 127) : 256 * ((dr - DFF) >> 7) + 128 + ((dr - DFF) & 127); }
;         if (MODE == 2) {
;             if (dr >= 6144) { const int t = dr - 6144, ch = t & 2047; dr = 6144 + 256 * (ch >> 7) + ((t >> 11) << 7) + (ch & 127); }
;             else if (dr >= 4096) { const int t = dr - 4096, ch = t & 1023; dr = 4096 + 256 * (ch >> 7) + ((t >> 10) << 7) + (ch & 127); }
;         }
;         *(u32x4*)(WT + (size_t)dr * ldt + coff + k0 + 8 * c) = o;
;     }
;     asm volatile("s_waitcnt lgkmcnt(0)" ::: "memory");
.Ltr_pr2_p3dn:
	s_add_u32 s9, s9, 0x400
	s_lshr_b32 s11, s10, 6
	s_and_b32 s34, s10, 0x3f
	s_mul_i32 s35, s34, 0x58000
	s_lshl_b32 s11, s11, 7
	s_add_u32 s35, s35, s11
	s_add_u32 s32, s6, s35
	s_addc_u32 s33, s7, 0
	ds_write_b32 v159, v64 offset:0
	ds_write_b32 v159, v65 offset:4
	ds_write_b32 v159, v66 offset:8
	ds_write_b32 v159, v67 offset:12
	ds_write_b32 v159, v68 offset:1056
	ds_write_b32 v159, v69 offset:1060
	ds_write_b32 v159, v70 offset:1064
	ds_write_b32 v159, v71 offset:1068
	ds_write_b32 v159, v72 offset:2112
	ds_write_b32 v159, v73 offset:2116
	ds_write_b32 v159, v74 offset:2120
	ds_write_b32 v159, v75 offset:2124
	ds_write_b32 v159, v76 offset:3168
	ds_write_b32 v159, v77 offset:3172
	ds_write_b32 v159, v78 offset:3176
	ds_write_b32 v159, v79 offset:3180
	ds_write_b32 v159, v80 offset:4224
	ds_write_b32 v159, v81 offset:4228
	ds_write_b32 v159, v82 offset:4232
	ds_write_b32 v159, v83 offset:4236
	ds_write_b32 v159, v84 offset:5280
	ds_write_b32 v159, v85 offset:5284
	ds_write_b32 v159, v86 offset:5288
	ds_write_b32 v159, v87 offset:5292
	ds_write_b32 v159, v88 offset:6336
	ds_write_b32 v159, v89 offset:6340
	ds_write_b32 v159, v90 offset:6344
	ds_write_b32 v159, v91 offset:6348
	ds_write_b32 v159, v92 offset:7392
	ds_write_b32 v159, v93 offset:7396
	ds_write_b32 v159, v94 offset:7400
	ds_write_b32 v159, v95 offset:7404
	s_waitcnt lgkmcnt(0)
	ds_read2_b32 v[96:97], v160 offset0:0 offset1:8
	ds_read2_b32 v[100:101], v160 offset0:33 offset1:41
	ds_read2_b32 v[104:105], v160 offset0:66 offset1:74
	ds_read2_b32 v[108:109], v160 offset0:99 offset1:107
	ds_read2_b32 v[112:113], v160 offset0:132 offset1:140
	ds_read2_b32 v[116:117], v160 offset0:165 offset1:173
	ds_read2_b32 v[120:121], v160 offset0:198 offset1:206
	ds_read2_b32 v[124:125], v160 offset0:231 offset1:239
	ds_read2_b32 v[98:99], v160 offset0:16 offset1:24
	ds_read2_b32 v[102:103], v160 offset0:49 offset1:57
	ds_read2_b32 v[106:107], v160 offset0:82 offset1:90
	ds_read2_b32 v[110:111], v160 offset0:115 offset1:123
	ds_read2_b32 v[114:115], v160 offset0:148 offset1:156
	ds_read2_b32 v[118:119], v160 offset0:181 offset1:189
	ds_read2_b32 v[122:123], v160 offset0:214 offset1:222
	ds_read2_b32 v[126:127], v160 offset0:247 offset1:255
	s_waitcnt lgkmcnt(0)
	v_cvt_pk_bf16_f32 v128, v96, v100
	v_cvt_pk_bf16_f32 v129, v104, v108
	v_cvt_pk_bf16_f32 v130, v112, v116
	v_cvt_pk_bf16_f32 v131, v120, v124
	global_store_dwordx4 v155, v[128:131], s[32:33]
	v_cvt_pk_bf16_f32 v132, v97, v101
	v_cvt_pk_bf16_f32 v133, v105, v109
	v_cvt_pk_bf16_f32 v134, v113, v117
	v_cvt_pk_bf16_f32 v135, v121, v125
	global_store_dwordx4 v156, v[132:135], s[32:33]
	v_cvt_pk_bf16_f32 v136, v98, v102
	v_cvt_pk_bf16_f32 v137, v106, v110
	v_cvt_pk_bf16_f32 v138, v114, v118
	v_cvt_pk_bf16_f32 v139, v122, v126
	global_store_dwordx4 v157, v[136:139], s[32:33]
	v_cvt_pk_bf16_f32 v140, v99, v103
	v_cvt_pk_bf16_f32 v141, v107, v111
	v_cvt_pk_bf16_f32 v142, v115, v119
	v_cvt_pk_bf16_f32 v143, v123, v127
	global_store_dwordx4 v158, v[140:143], s[32:33]
	s_add_u32 s10, s10, 0x400
	s_cmp_lt_u32 s10, 0x1600
	s_cbranch_scc0 .Ltr_done_p3dn
	s_branch .Ltr_st0_p3dn
.Ltr_done_p3dn:
	s_waitcnt lgkmcnt(0)
.LBB0_670:
	s_cmpk_lt_i32 s2, 0x80
	v_readlane_b32 s6, v250, 24
	s_cselect_b64 s[0:1], -1, 0
	v_readlane_b32 s7, v250, 25
	s_and_b64 s[0:1], s[0:1], s[6:7]
	s_and_b64 vcc, exec, s[0:1]
	s_barrier
	s_cbranch_vccnz .LBB0_672
	v_lshrrev_b32_e32 v3, 1, v179
	v_lshrrev_b32_e32 v4, 5, v179
	v_and_b32_e32 v3, 24, v3
	v_and_b32_e32 v4, 4, v4
	v_bfe_u32 v5, v179, 2, 2
	v_lshlrev_b32_e32 v0, 4, v179
	v_and_b32_e32 v1, 32, v179
	v_bfe_u32 v2, v179, 2, 4
	v_or3_b32 v3, v4, v5, v3
	v_lshrrev_b32_e32 v4, 3, v179
	s_movk_i32 s0, 0x70
	v_bitop3_b32 v1, v0, v1, 48 bitop3:0x6c
	v_and_or_b32 v5, v4, s0, v2
	s_movk_i32 s0, 0x60
	v_add_u32_e32 v0, 0x2000, v0
	v_and_or_b32 v4, v4, s0, v3
	v_lshrrev_b32_e32 v0, 7, v0
	s_movk_i32 s0, 0xf0
	v_and_or_b32 v2, v0, s0, v2
	s_movk_i32 s0, 0xe0
	v_and_or_b32 v1, v179, 64, v1
	v_and_or_b32 v0, v0, s0, v3
	v_lshl_or_b32 v134, v0, 12, v1
	v_bfe_u32 v0, v179, 4, 2
	v_lshl_or_b32 v128, v5, 12, v1
	v_lshl_or_b32 v130, v4, 12, v1
	v_lshl_or_b32 v132, v2, 12, v1
	v_lshlrev_b32_e32 v32, 3, v0
	v_lshlrev_b32_e32 v51, 4, v0
	v_lshlrev_b32_e32 v0, 6, v179
	v_lshlrev_b32_e32 v1, 2, v179
	v_and_b32_e32 v0, 0x3c0, v0
	v_and_b32_e32 v1, 32, v1
	v_and_b32_e32 v50, 15, v179
	v_bitop3_b32 v52, v51, v1, v0 bitop3:0x36
	s_cbranch_execz .LBB0_673
	s_branch .LBB0_694
